# exact counted vmcnt waits in flash staging loops (phase C passes, selected branch) when the other register set's loads are in flight
# speedup vs baseline: 1.0197x; 1.0028x over previous
.LBB0_489:
	s_add_i32 s77, s75, -4
	s_cmp_lt_u32 s77, s73
	s_cselect_b64 s[68:69], -1, 0
	s_cmp_ge_u32 s77, s73
	s_cbranch_scc1 .LBB0_491
	s_add_i32 s75, s75, -2
	s_cmp_le_u32 s75, s73
	s_cbranch_scc1 .Lvr_p1a
	s_add_i32 s75, s75, 2
	s_waitcnt vmcnt(1)
	ds_write_b128 v42, v[16:19] offset:16384
	s_waitcnt vmcnt(0)
	ds_write_b128 v42, v[20:23] offset:24576
	s_branch .LBB0_491
.Lvr_p1a:
	s_add_i32 s75, s75, 2
	s_waitcnt vmcnt(3)
	ds_write_b128 v42, v[16:19] offset:16384
	s_waitcnt vmcnt(2)
	ds_write_b128 v42, v[20:23] offset:24576

.LBB0_501:
	v_cvt_pk_bf16_f32 v0, v0, v1
	v_cvt_pk_bf16_f32 v1, v2, v3
	v_cvt_pk_bf16_f32 v2, v4, v5
	v_cvt_pk_bf16_f32 v3, v6, v7
	s_waitcnt lgkmcnt(0)
	s_andn2_b64 vcc, exec, s[68:69]
	s_barrier
	v_mfma_f32_16x16x32_bf16 v[50:53], v[32:35], v[0:3], v[36:39]
	s_cbranch_vccnz .LBB0_488
	s_add_i32 s2, s75, -2
	s_cmp_gt_u32 s2, s73
	s_cbranch_scc1 .LBB0_504
	s_add_i32 s75, s75, -1
	s_cmp_le_u32 s75, s73
	s_cbranch_scc1 .Lvr_p1b
	s_add_i32 s75, s75, 1
	s_waitcnt vmcnt(1)
	ds_write_b128 v42, v[8:11]
	s_waitcnt vmcnt(0)
	ds_write_b128 v42, v[12:15] offset:8192
	s_branch .LBB0_504
.Lvr_p1b:
	s_add_i32 s75, s75, 1
	s_waitcnt vmcnt(3)
	ds_write_b128 v42, v[8:11]
	s_waitcnt vmcnt(2)
	ds_write_b128 v42, v[12:15] offset:8192

.LBB0_521:
	s_cmp_lt_u32 s69, s73
	s_cselect_b64 s[62:63], -1, 0
	s_cmp_ge_u32 s69, s73
	s_cbranch_scc1 .LBB0_523
	s_add_i32 s69, s69, 2
	s_cmp_le_u32 s69, s73
	s_cbranch_scc1 .Lvr_p2a
	s_add_i32 s69, s69, -2
	s_waitcnt vmcnt(3)
	ds_write_b128 v108, v[20:23] offset:16384
	s_waitcnt vmcnt(2)
	ds_write_b128 v108, v[28:31] offset:24576
	s_waitcnt vmcnt(1)
	ds_write_b128 v109, v[32:35] offset:20480
	s_waitcnt vmcnt(0)
	ds_write_b128 v109, v[36:39] offset:28672
	s_branch .LBB0_523
.Lvr_p2a:
	s_add_i32 s69, s69, -2
	s_waitcnt vmcnt(7)
	ds_write_b128 v108, v[20:23] offset:16384
	s_waitcnt vmcnt(6)
	ds_write_b128 v108, v[28:31] offset:24576
	s_waitcnt vmcnt(5)
	ds_write_b128 v109, v[32:35] offset:20480
	s_waitcnt vmcnt(4)
	ds_write_b128 v109, v[36:39] offset:28672

.LBB0_545:
	s_or_b64 exec, exec, s[64:65]
	v_cvt_pk_bf16_f32 v0, v0, v1
	v_cvt_pk_bf16_f32 v1, v2, v3
	v_cvt_pk_bf16_f32 v2, v4, v5
	v_cvt_pk_bf16_f32 v3, v6, v7
	s_waitcnt lgkmcnt(0)
	s_andn2_b64 vcc, exec, s[62:63]
	s_barrier
	s_waitcnt lgkmcnt(3)
	v_mfma_f32_16x16x32_bf16 v[48:51], v[72:75], v[0:3], v[48:51]
	s_waitcnt lgkmcnt(2)
	v_mfma_f32_16x16x32_bf16 v[56:59], v[76:79], v[0:3], v[56:59]
	s_waitcnt lgkmcnt(1)
	v_mfma_f32_16x16x32_bf16 v[52:55], v[68:71], v[0:3], v[52:55]
	s_waitcnt lgkmcnt(0)
	v_mfma_f32_16x16x32_bf16 v[60:63], v[64:67], v[0:3], v[60:63]
	s_cbranch_vccnz .LBB0_520
	s_add_i32 s2, s69, 2
	s_cmp_gt_u32 s2, s73
	s_cbranch_scc1 .LBB0_548
	s_add_i32 s69, s69, 3
	s_cmp_le_u32 s69, s73
	s_cbranch_scc1 .Lvr_p2b
	s_add_i32 s69, s69, -3
	s_waitcnt vmcnt(3)
	ds_write_b128 v108, v[8:11]
	s_waitcnt vmcnt(2)
	ds_write_b128 v108, v[12:15] offset:8192
	s_waitcnt vmcnt(1)
	ds_write_b128 v109, v[16:19] offset:4096
	s_waitcnt vmcnt(0)
	ds_write_b128 v109, v[24:27] offset:12288
	s_branch .LBB0_548
.Lvr_p2b:
	s_add_i32 s69, s69, -3
	s_waitcnt vmcnt(7)
	ds_write_b128 v108, v[8:11]
	s_waitcnt vmcnt(6)
	ds_write_b128 v108, v[12:15] offset:8192
	s_waitcnt vmcnt(5)
	ds_write_b128 v109, v[16:19] offset:4096
	s_waitcnt vmcnt(4)
	ds_write_b128 v109, v[24:27] offset:12288

.LBB0_756:
	s_add_i32 s42, s27, -4
	s_cmp_lt_u32 s42, s69
	s_cselect_b64 s[40:41], -1, 0
	s_cmp_ge_u32 s42, s69
	s_cbranch_scc1 .LBB0_758
	s_add_i32 s27, s27, -2
	s_cmp_le_u32 s27, s69
	s_cbranch_scc1 .Lvr_sa
	s_add_i32 s27, s27, 2
	s_waitcnt vmcnt(3)
	ds_write_b128 v242, v[76:79] offset:16384
	s_waitcnt vmcnt(2)
	ds_write_b128 v242, v[80:83] offset:24576
	s_waitcnt vmcnt(1)
	ds_write_b128 v243, v[88:91] offset:20480
	s_waitcnt vmcnt(0)
	ds_write_b128 v243, v[92:95] offset:28672
	s_branch .LBB0_758
.Lvr_sa:
	s_add_i32 s27, s27, 2
	s_waitcnt vmcnt(7)
	ds_write_b128 v242, v[76:79] offset:16384
	s_waitcnt vmcnt(6)
	ds_write_b128 v242, v[80:83] offset:24576
	s_waitcnt vmcnt(5)
	ds_write_b128 v243, v[88:91] offset:20480
	s_waitcnt vmcnt(4)
	ds_write_b128 v243, v[92:95] offset:28672

.LBB0_810:
	s_waitcnt lgkmcnt(0)
	s_andn2_b64 vcc, exec, s[40:41]
	s_barrier
	s_cbranch_vccnz .LBB0_755
	s_add_i32 s2, s27, -2
	s_cmp_gt_u32 s2, s69
	s_cbranch_scc1 .LBB0_813
	s_add_i32 s27, s27, -1
	s_cmp_le_u32 s27, s69
	s_cbranch_scc1 .Lvr_sb
	s_add_i32 s27, s27, 1
	s_waitcnt vmcnt(3)
	ds_write_b128 v242, v[56:59]
	s_waitcnt vmcnt(2)
	ds_write_b128 v242, v[68:71] offset:8192
	s_waitcnt vmcnt(1)
	ds_write_b128 v243, v[84:87] offset:4096
	s_waitcnt vmcnt(0)
	ds_write_b128 v243, v[96:99] offset:12288
	s_branch .LBB0_813
.Lvr_sb:
	s_add_i32 s27, s27, 1
	s_waitcnt vmcnt(7)
	ds_write_b128 v242, v[56:59]
	s_waitcnt vmcnt(6)
	ds_write_b128 v242, v[68:71] offset:8192
	s_waitcnt vmcnt(5)
	ds_write_b128 v243, v[84:87] offset:4096
	s_waitcnt vmcnt(4)
	ds_write_b128 v243, v[96:99] offset:12288
